# grid barrier rewritten: first sync uses counter barrier + census, later syncs XCD-hierarchical (one L2 writeback per XCC, release-only arrive, acquire-only depart); GEMM epilogue rcp
# speedup vs baseline: 1.0235x; 1.0235x over previous
; __device__ __forceinline__ void grid_barrier(unsigned* ctr, unsigned target) {
;     asm volatile("s_waitcnt vmcnt(0)" ::: "memory");
;     __syncthreads();
;     if (threadIdx.x == 0) {
;         __threadfence();
;         asm volatile("s_waitcnt vmcnt(0)" ::: "memory");
;         __hip_atomic_fetch_add(ctr, 1u, __ATOMIC_RELAXED, __HIP_MEMORY_SCOPE_AGENT);
;         while (__hip_atomic_load(ctr, __ATOMIC_RELAXED, __HIP_MEMORY_SCOPE_AGENT) < target) __builtin_amdgcn_s_sleep(1);
;         __threadfence();
;         asm volatile("s_waitcnt vmcnt(0)" ::: "memory");
;     }
;     __syncthreads();
; }
; __global__ void __launch_bounds__(NTHR) fwd_megakernel(Params p) {
;     ...
;     for (int ph = p.ph_lo; ph < p.ph_hi; ++ph) {
;         run_phase(p, ph, lds);
;         if (ph + 1 < p.ph_hi) {
;             if (ph == p.ph_lo) cg::this_grid().sync();
;             else { ++nbar; grid_barrier(ctr, nbar * gridDim.x); }
;         }
;     }
.LBB0_727:
	v_readlane_b32 s2, v255, 9
	v_readlane_b32 s0, v253, 1
	s_add_i32 s8, s2, 1
	v_readlane_b32 s1, v253, 2
	v_readlane_b32 s12, v254, 60
	s_cmp_ge_i32 s8, s1
	s_mov_b64 s[0:1], -1
	v_readlane_b32 s13, v254, 61
	v_readlane_b32 s9, v254, 62
	s_cbranch_scc1 .LBB0_5
	v_readlane_b32 s0, v253, 1
	v_readlane_b32 s1, v253, 2
	s_cmp_lg_u32 s2, s0
	s_mov_b64 s[0:1], -1
	s_waitcnt vmcnt(0)
	s_add_i32 s6, s93, 1
	s_waitcnt vmcnt(0)
	s_barrier
	s_mov_b64 s[0:1], exec
	v_readlane_b32 s2, v254, 6
	v_readlane_b32 s3, v254, 7
	s_and_b64 s[2:3], s[0:1], s[2:3]
	s_mov_b64 exec, s[2:3]
	s_cbranch_execz .LBB0_735
	s_getreg_b32 s10, hwreg(HW_REG_XCC_ID, 0, 4)
	s_lshl_b32 s10, s10, 6
	v_mov_b32_e32 v1, 1
	v_mov_b32_e32 v2, s10
	s_cmp_lg_u32 s6, 1
	s_cbranch_scc1 .Lxb_hier
	global_atomic_add v2, v1, s[12:13] offset:256
	buffer_wbl2 sc1
	s_waitcnt vmcnt(0)
	global_atomic_add v133, v1, s[12:13]
	s_load_dword s2, s[28:29], 0x0
	s_waitcnt lgkmcnt(0)
.Lxb_flat_wait:
	s_sleep 1
	global_load_dword v0, v133, s[12:13] sc1
	s_waitcnt vmcnt(0)
	v_cmp_gt_u32_e32 vcc, s2, v0
	s_cbranch_vccnz .Lxb_flat_wait
	buffer_inv sc1
	s_waitcnt vmcnt(0)
	global_load_dword v0, v2, s[12:13] offset:256 sc1
	s_waitcnt vmcnt(0)
	v_readfirstlane_b32 s4, v0
	s_mov_b32 s5, 0
	global_load_dword v0, v133, s[12:13] offset:256 sc1
	s_waitcnt vmcnt(0)
	v_readfirstlane_b32 s3, v0
	s_cmp_lg_u32 s3, 0
	s_addc_u32 s5, s5, 0
	global_load_dword v0, v133, s[12:13] offset:320 sc1
	s_waitcnt vmcnt(0)
	v_readfirstlane_b32 s3, v0
	s_cmp_lg_u32 s3, 0
	s_addc_u32 s5, s5, 0
	global_load_dword v0, v133, s[12:13] offset:384 sc1
	s_waitcnt vmcnt(0)
	v_readfirstlane_b32 s3, v0
	s_cmp_lg_u32 s3, 0
	s_addc_u32 s5, s5, 0
	global_load_dword v0, v133, s[12:13] offset:448 sc1
	s_waitcnt vmcnt(0)
	v_readfirstlane_b32 s3, v0
	s_cmp_lg_u32 s3, 0
	s_addc_u32 s5, s5, 0
	global_load_dword v0, v133, s[12:13] offset:512 sc1
	s_waitcnt vmcnt(0)
	v_readfirstlane_b32 s3, v0
	s_cmp_lg_u32 s3, 0
	s_addc_u32 s5, s5, 0
	global_load_dword v0, v133, s[12:13] offset:576 sc1
	s_waitcnt vmcnt(0)
	v_readfirstlane_b32 s3, v0
	s_cmp_lg_u32 s3, 0
	s_addc_u32 s5, s5, 0
	global_load_dword v0, v133, s[12:13] offset:640 sc1
	s_waitcnt vmcnt(0)
	v_readfirstlane_b32 s3, v0
	s_cmp_lg_u32 s3, 0
	s_addc_u32 s5, s5, 0
	global_load_dword v0, v133, s[12:13] offset:704 sc1
	s_waitcnt vmcnt(0)
	v_readfirstlane_b32 s3, v0
	s_cmp_lg_u32 s3, 0
	s_addc_u32 s5, s5, 0
	global_load_dword v0, v133, s[12:13] offset:768 sc1
	s_waitcnt vmcnt(0)
	v_readfirstlane_b32 s3, v0
	s_cmp_lg_u32 s3, 0
	s_addc_u32 s5, s5, 0
	global_load_dword v0, v133, s[12:13] offset:832 sc1
	s_waitcnt vmcnt(0)
	v_readfirstlane_b32 s3, v0
	s_cmp_lg_u32 s3, 0
	s_addc_u32 s5, s5, 0
	global_load_dword v0, v133, s[12:13] offset:896 sc1
	s_waitcnt vmcnt(0)
	v_readfirstlane_b32 s3, v0
	s_cmp_lg_u32 s3, 0
	s_addc_u32 s5, s5, 0
	global_load_dword v0, v133, s[12:13] offset:960 sc1
	s_waitcnt vmcnt(0)
	v_readfirstlane_b32 s3, v0
	s_cmp_lg_u32 s3, 0
	s_addc_u32 s5, s5, 0
	global_load_dword v0, v133, s[12:13] offset:1024 sc1
	s_waitcnt vmcnt(0)
	v_readfirstlane_b32 s3, v0
	s_cmp_lg_u32 s3, 0
	s_addc_u32 s5, s5, 0
	global_load_dword v0, v133, s[12:13] offset:1088 sc1
	s_waitcnt vmcnt(0)
	v_readfirstlane_b32 s3, v0
	s_cmp_lg_u32 s3, 0
	s_addc_u32 s5, s5, 0
	global_load_dword v0, v133, s[12:13] offset:1152 sc1
	s_waitcnt vmcnt(0)
	v_readfirstlane_b32 s3, v0
	s_cmp_lg_u32 s3, 0
	s_addc_u32 s5, s5, 0
	global_load_dword v0, v133, s[12:13] offset:1216 sc1
	s_waitcnt vmcnt(0)
	v_readfirstlane_b32 s3, v0
	s_cmp_lg_u32 s3, 0
	s_addc_u32 s5, s5, 0
	v_writelane_b32 v255, s4, 15
	v_writelane_b32 v255, s5, 16
	s_branch .LBB0_735
.Lxb_hier:
	s_add_i32 s7, s6, -1
	global_atomic_add v0, v2, v1, s[12:13] offset:1280 sc0
	v_readlane_b32 s11, v255, 15
	s_mov_b32 s5, 0
	s_mul_i32 s11, s11, s7
	s_waitcnt vmcnt(0)
	v_add_u32_e32 v0, 1, v0
	v_cmp_eq_u32_e32 vcc, s11, v0
	s_cbranch_vccz .Lxb_follower
	buffer_wbl2 sc1
	s_waitcnt vmcnt(0)
	global_atomic_add v0, v133, v1, s[12:13] offset:3456 sc0
	v_readlane_b32 s11, v255, 16
	s_nop 0
	s_mul_i32 s11, s11, s7
	s_waitcnt vmcnt(0)
	v_add_u32_e32 v0, 1, v0
	v_cmp_eq_u32_e32 vcc, s11, v0
	s_cbranch_vccz .Lxb_wait_top
	global_atomic_add v133, v1, s[12:13] offset:3584
	s_branch .Lxb_top_done
.Lxb_wait_top:
	s_sleep 1
	global_load_dword v0, v133, s[12:13] offset:3584 sc1
	s_add_i32 s5, s5, 1
	s_waitcnt vmcnt(0)
	v_cmp_gt_u32_e32 vcc, s7, v0
	s_cbranch_vccz .Lxb_top_done
	s_cmp_lt_u32 s5, 0x10000
	s_cbranch_scc1 .Lxb_wait_top
.Lxb_top_done:
	buffer_inv sc1
	global_atomic_add v2, v1, s[12:13] offset:2304
	s_waitcnt vmcnt(0)
	s_branch .LBB0_735
.Lxb_follower:
	s_sleep 1
	global_load_dword v0, v2, s[12:13] offset:2304 sc1
	s_add_i32 s5, s5, 1
	s_waitcnt vmcnt(0)
	v_cmp_gt_u32_e32 vcc, s7, v0
	s_cbranch_vccz .Lxb_fol_done
	s_cmp_lt_u32 s5, 0x10000
	s_cbranch_scc1 .Lxb_follower
.Lxb_fol_done:
	buffer_inv sc1
	s_waitcnt vmcnt(0)
